# skinny (sample-row) GEMM K loops unrolled by hand: up to 11 fragment pairs in flight under counted vmcnt instead of a full memory round trip per MFMA (6 loops)
# speedup vs baseline: 1.0021x; 1.0021x over previous
; template <int MODE>
; __device__ __forceinline__ void skinny_rows(Frame& F, const bf16* A, size_t sA, const bf16* Bt, size_t sB, int K, const bf16* G, bf16* MB, const void* res, int rb16, float* out, bf16* Hn, float* rs) {
;     ...
;     const int nks = K / 32;
; #pragma unroll
;     for (int b = 0; b < NBR; ++b) {
;         acc[b] = (f32x4){0.f, 0.f, 0.f, 0.f};
;         const bf16* ap = A + (size_t)b * sA + (size_t)(MP + 16 * rt + li) * K + 8 * q;
;         const bf16* bp = Bt + (size_t)b * sB + (size_t)(16 * ct + li) * K + 8 * q;
; #pragma unroll 4
;         for (int ks = w; ks < nks; ks += 8) {
;             const bf16x8 av = *(const bf16x8*)(ap + 32 * ks), bv = *(const bf16x8*)(bp + 32 * ks);
;             acc[b] = __builtin_amdgcn_mfma_f32_16x16x32_bf16(bv, av, acc[b], 0, 0, 0);
;         }
;         red[(w * NBR + b) * 64 + lane] = acc[b];
.LBB0_1398:
	s_lshl_b32 s0, s20, 6
	s_mov_b32 s1, 0
	v_lshl_add_u64 v[44:45], v[14:15], 0, s[0:1]
	v_lshl_add_u64 v[46:47], v[6:7], 0, s[0:1]
	global_load_dwordx4 v[24:27], v[44:45], off
	global_load_dwordx4 v[28:31], v[46:47], off
	global_load_dwordx4 v[36:39], v[44:45], off offset:512
	global_load_dwordx4 v[40:43], v[46:47], off offset:512
	s_waitcnt vmcnt(2)
	v_mfma_f32_16x16x32_bf16 v[2:5], v[24:27], v[28:31], v[2:5]
	s_waitcnt vmcnt(0)
	v_mfma_f32_16x16x32_bf16 v[2:5], v[36:39], v[40:43], v[2:5]
	s_add_i32 s12, s20, 8
	s_lshl_b32 s0, s20, 5
	s_addk_i32 s0, 0x200
	s_add_i32 s14, s0, 0xffffff00
	s_lshl_b32 s14, s14, 1
	s_mov_b32 s15, 0

; template <int MODE>
; __device__ __forceinline__ void skinny_rows(Frame& F, const bf16* A, size_t sA, const bf16* Bt, size_t sB, int K, const bf16* G, bf16* MB, const void* res, int rb16, float* out, bf16* Hn, float* rs) {
;     ...
; #pragma unroll
;     for (int b = 0; b < NBR; ++b) {
;         acc[b] = (f32x4){0.f, 0.f, 0.f, 0.f};
;         const bf16* ap = A + (size_t)b * sA + (size_t)(MP + 16 * rt + li) * K + 8 * q;
;         const bf16* bp = Bt + (size_t)b * sB + (size_t)(16 * ct + li) * K + 8 * q;
; #pragma unroll 4
;         for (int ks = w; ks < nks; ks += 8) {
;             const bf16x8 av = *(const bf16x8*)(ap + 32 * ks), bv = *(const bf16x8*)(bp + 32 * ks);
;             acc[b] = __builtin_amdgcn_mfma_f32_16x16x32_bf16(bv, av, acc[b], 0, 0, 0);
;         }
;         red[(w * NBR + b) * 64 + lane] = acc[b];
.LBB0_1401:
	s_lshl_b32 s2, s20, 6
	s_mov_b32 s3, 0
	v_lshl_add_u64 v[48:49], v[4:5], 0, s[2:3]
	v_lshl_add_u64 v[50:51], v[2:3], 0, s[2:3]
	global_load_dwordx4 v[28:31], v[48:49], off
	global_load_dwordx4 v[36:39], v[50:51], off
	global_load_dwordx4 v[40:43], v[48:49], off offset:512
	global_load_dwordx4 v[44:47], v[50:51], off offset:512
	s_waitcnt vmcnt(2)
	v_mfma_f32_16x16x32_bf16 v[10:13], v[28:31], v[36:39], v[10:13]
	s_waitcnt vmcnt(0)
	v_mfma_f32_16x16x32_bf16 v[10:13], v[40:43], v[44:47], v[10:13]
	s_add_i32 s12, s20, 8
	s_lshl_b32 s2, s20, 5
	s_addk_i32 s2, 0x200
	s_add_i32 s14, s2, 0xffffff00
	s_lshl_b32 s14, s14, 1
	s_mov_b32 s15, 0
	s_branch .LBB0_1403

; template <int MODE>
; __device__ __forceinline__ void skinny_rows(Frame& F, const bf16* A, size_t sA, const bf16* Bt, size_t sB, int K, const bf16* G, bf16* MB, const void* res, int rb16, float* out, bf16* Hn, float* rs) {
;     ...
; #pragma unroll
;     for (int b = 0; b < NBR; ++b) {
;         acc[b] = (f32x4){0.f, 0.f, 0.f, 0.f};
;         const bf16* ap = A + (size_t)b * sA + (size_t)(MP + 16 * rt + li) * K + 8 * q;
;         const bf16* bp = Bt + (size_t)b * sB + (size_t)(16 * ct + li) * K + 8 * q;
; #pragma unroll 4
;         for (int ks = w; ks < nks; ks += 8) {
;             const bf16x8 av = *(const bf16x8*)(ap + 32 * ks), bv = *(const bf16x8*)(bp + 32 * ks);
;             acc[b] = __builtin_amdgcn_mfma_f32_16x16x32_bf16(bv, av, acc[b], 0, 0, 0);
;         }
;         red[(w * NBR + b) * 64 + lane] = acc[b];
.LBB0_1405:
	s_lshl_b32 s2, s20, 6
	s_mov_b32 s3, 0
	v_lshl_add_u64 v[48:49], v[8:9], 0, s[2:3]
	v_lshl_add_u64 v[50:51], v[6:7], 0, s[2:3]
	global_load_dwordx4 v[28:31], v[48:49], off
	global_load_dwordx4 v[36:39], v[50:51], off
	global_load_dwordx4 v[40:43], v[48:49], off offset:512
	global_load_dwordx4 v[44:47], v[50:51], off offset:512
	s_waitcnt vmcnt(2)
	v_mfma_f32_16x16x32_bf16 v[2:5], v[28:31], v[36:39], v[2:5]
	s_waitcnt vmcnt(0)
	v_mfma_f32_16x16x32_bf16 v[2:5], v[40:43], v[44:47], v[2:5]
	s_add_i32 s12, s20, 8
	s_lshl_b32 s2, s20, 5
	s_addk_i32 s2, 0x200
	s_add_i32 s14, s2, 0xffffff00
	s_lshl_b32 s14, s14, 1
	s_mov_b32 s15, 0
	v_mov_b32_e32 v6, s21
	v_mov_b32_e32 v7, s21
	v_mov_b32_e32 v8, s21
	v_mov_b32_e32 v9, s21

; template <int MODE>
; __device__ __forceinline__ void skinny_rows(Frame& F, const bf16* A, size_t sA, const bf16* Bt, size_t sB, int K, const bf16* G, bf16* MB, const void* res, int rb16, float* out, bf16* Hn, float* rs) {
;     ...
; #pragma unroll
;     for (int b = 0; b < NBR; ++b) {
;         acc[b] = (f32x4){0.f, 0.f, 0.f, 0.f};
;         const bf16* ap = A + (size_t)b * sA + (size_t)(MP + 16 * rt + li) * K + 8 * q;
;         const bf16* bp = Bt + (size_t)b * sB + (size_t)(16 * ct + li) * K + 8 * q;
; #pragma unroll 4
;         for (int ks = w; ks < nks; ks += 8) {
;             const bf16x8 av = *(const bf16x8*)(ap + 32 * ks), bv = *(const bf16x8*)(bp + 32 * ks);
;             acc[b] = __builtin_amdgcn_mfma_f32_16x16x32_bf16(bv, av, acc[b], 0, 0, 0);
;         }
;         red[(w * NBR + b) * 64 + lane] = acc[b];
.LBB0_1409:
	s_lshl_b32 s0, s20, 6
	s_mov_b32 s1, 0
	v_lshl_add_u64 v[44:45], v[4:5], 0, s[0:1]
	v_lshl_add_u64 v[46:47], v[2:3], 0, s[0:1]
	global_load_dwordx4 v[24:27], v[44:45], off
	global_load_dwordx4 v[28:31], v[46:47], off
	global_load_dwordx4 v[36:39], v[44:45], off offset:512
	global_load_dwordx4 v[40:43], v[46:47], off offset:512
	s_waitcnt vmcnt(2)
	v_mfma_f32_16x16x32_bf16 v[6:9], v[24:27], v[28:31], v[6:9]
	s_waitcnt vmcnt(0)
	v_mfma_f32_16x16x32_bf16 v[6:9], v[36:39], v[40:43], v[6:9]
	s_add_i32 s2, s20, 8
	s_lshl_b32 s0, s20, 5
	s_addk_i32 s0, 0x200
	s_add_i32 s12, s0, 0xffffff00
	s_lshl_b32 s12, s12, 1
	s_mov_b32 s13, 0

; template <int MODE>
; __device__ __forceinline__ void skinny_rows(Frame& F, const bf16* A, size_t sA, const bf16* Bt, size_t sB, int K, const bf16* G, bf16* MB, const void* res, int rb16, float* out, bf16* Hn, float* rs) {
;     ...
; #pragma unroll
;     for (int b = 0; b < NBR; ++b) {
;         acc[b] = (f32x4){0.f, 0.f, 0.f, 0.f};
;         const bf16* ap = A + (size_t)b * sA + (size_t)(MP + 16 * rt + li) * K + 8 * q;
;         const bf16* bp = Bt + (size_t)b * sB + (size_t)(16 * ct + li) * K + 8 * q;
; #pragma unroll 4
;         for (int ks = w; ks < nks; ks += 8) {
;             const bf16x8 av = *(const bf16x8*)(ap + 32 * ks), bv = *(const bf16x8*)(bp + 32 * ks);
;             acc[b] = __builtin_amdgcn_mfma_f32_16x16x32_bf16(bv, av, acc[b], 0, 0, 0);
;         }
;         red[(w * NBR + b) * 64 + lane] = acc[b];
.LBB0_1529:
	s_lshl_b32 s0, s20, 6
	s_mov_b32 s1, 0
	v_lshl_add_u64 v[92:93], v[8:9], 0, s[0:1]
	v_lshl_add_u64 v[94:95], v[6:7], 0, s[0:1]
	global_load_dwordx4 v[20:23], v[92:93], off
	global_load_dwordx4 v[24:27], v[94:95], off
	global_load_dwordx4 v[28:31], v[92:93], off offset:512
	global_load_dwordx4 v[40:43], v[94:95], off offset:512
	global_load_dwordx4 v[44:47], v[92:93], off offset:1024
	global_load_dwordx4 v[48:51], v[94:95], off offset:1024
	global_load_dwordx4 v[52:55], v[92:93], off offset:1536
	global_load_dwordx4 v[56:59], v[94:95], off offset:1536
	global_load_dwordx4 v[60:63], v[92:93], off offset:2048
	global_load_dwordx4 v[64:67], v[94:95], off offset:2048
	global_load_dwordx4 v[68:71], v[92:93], off offset:2560
	global_load_dwordx4 v[72:75], v[94:95], off offset:2560
	global_load_dwordx4 v[76:79], v[92:93], off offset:3072
	global_load_dwordx4 v[80:83], v[94:95], off offset:3072
	global_load_dwordx4 v[84:87], v[92:93], off offset:3584
	global_load_dwordx4 v[88:91], v[94:95], off offset:3584
	s_waitcnt vmcnt(14)
	v_mfma_f32_16x16x32_bf16 v[2:5], v[20:23], v[24:27], v[2:5]
	s_waitcnt vmcnt(12)
	v_mfma_f32_16x16x32_bf16 v[2:5], v[28:31], v[40:43], v[2:5]
	s_waitcnt vmcnt(10)
	v_mfma_f32_16x16x32_bf16 v[2:5], v[44:47], v[48:51], v[2:5]
	s_waitcnt vmcnt(8)
	v_mfma_f32_16x16x32_bf16 v[2:5], v[52:55], v[56:59], v[2:5]
	s_waitcnt vmcnt(6)
	v_mfma_f32_16x16x32_bf16 v[2:5], v[60:63], v[64:67], v[2:5]
	s_waitcnt vmcnt(4)
	v_mfma_f32_16x16x32_bf16 v[2:5], v[68:71], v[72:75], v[2:5]
	s_waitcnt vmcnt(2)
	v_mfma_f32_16x16x32_bf16 v[2:5], v[76:79], v[80:83], v[2:5]
	s_waitcnt vmcnt(0)
	v_mfma_f32_16x16x32_bf16 v[2:5], v[84:87], v[88:91], v[2:5]
	s_add_i32 s12, s20, 56
	s_lshl_b32 s0, s20, 5
	s_addk_i32 s0, 0x800
	s_add_i32 s14, s0, 0xffffff00
	s_lshl_b32 s14, s14, 1
	s_mov_b32 s15, 0

; template <int MODE>
; __device__ __forceinline__ void skinny_rows(Frame& F, const bf16* A, size_t sA, const bf16* Bt, size_t sB, int K, const bf16* G, bf16* MB, const void* res, int rb16, float* out, bf16* Hn, float* rs) {
;     ...
; #pragma unroll
;     for (int b = 0; b < NBR; ++b) {
;         acc[b] = (f32x4){0.f, 0.f, 0.f, 0.f};
;         const bf16* ap = A + (size_t)b * sA + (size_t)(MP + 16 * rt + li) * K + 8 * q;
;         const bf16* bp = Bt + (size_t)b * sB + (size_t)(16 * ct + li) * K + 8 * q;
; #pragma unroll 4
;         for (int ks = w; ks < nks; ks += 8) {
;             const bf16x8 av = *(const bf16x8*)(ap + 32 * ks), bv = *(const bf16x8*)(bp + 32 * ks);
;             acc[b] = __builtin_amdgcn_mfma_f32_16x16x32_bf16(bv, av, acc[b], 0, 0, 0);
;         }
;         red[(w * NBR + b) * 64 + lane] = acc[b];
.LBB0_1779:
	s_lshl_b32 s2, s20, 6
	s_mov_b32 s3, 0
	v_lshl_add_u64 v[112:113], v[8:9], 0, s[2:3]
	v_lshl_add_u64 v[114:115], v[6:7], 0, s[2:3]
	s_movk_i32 s2, 0x1000
	v_lshl_add_u64 v[116:117], v[112:113], 0, s[2:3]
	v_lshl_add_u64 v[118:119], v[114:115], 0, s[2:3]
	v_lshl_add_u64 v[120:121], v[116:117], 0, s[2:3]
	v_lshl_add_u64 v[122:123], v[118:119], 0, s[2:3]
	global_load_dwordx4 v[20:23], v[112:113], off
	global_load_dwordx4 v[24:27], v[114:115], off
	global_load_dwordx4 v[28:31], v[112:113], off offset:512
	global_load_dwordx4 v[36:39], v[114:115], off offset:512
	global_load_dwordx4 v[40:43], v[112:113], off offset:1024
	global_load_dwordx4 v[44:47], v[114:115], off offset:1024
	global_load_dwordx4 v[48:51], v[112:113], off offset:1536
	global_load_dwordx4 v[52:55], v[114:115], off offset:1536
	global_load_dwordx4 v[56:59], v[112:113], off offset:2048
	global_load_dwordx4 v[60:63], v[114:115], off offset:2048
	global_load_dwordx4 v[64:67], v[112:113], off offset:2560
	global_load_dwordx4 v[68:71], v[114:115], off offset:2560
	global_load_dwordx4 v[72:75], v[112:113], off offset:3072
	global_load_dwordx4 v[76:79], v[114:115], off offset:3072
	global_load_dwordx4 v[80:83], v[112:113], off offset:3584
	global_load_dwordx4 v[84:87], v[114:115], off offset:3584
	global_load_dwordx4 v[88:91], v[116:117], off
	global_load_dwordx4 v[92:95], v[118:119], off
	global_load_dwordx4 v[96:99], v[116:117], off offset:512
	global_load_dwordx4 v[100:103], v[118:119], off offset:512
	global_load_dwordx4 v[104:107], v[116:117], off offset:1024
	global_load_dwordx4 v[108:111], v[118:119], off offset:1024
	s_waitcnt vmcnt(20)
	v_mfma_f32_16x16x32_bf16 v[2:5], v[20:23], v[24:27], v[2:5]
	global_load_dwordx4 v[20:23], v[116:117], off offset:1536
	global_load_dwordx4 v[24:27], v[118:119], off offset:1536
	s_waitcnt vmcnt(20)
	v_mfma_f32_16x16x32_bf16 v[2:5], v[28:31], v[36:39], v[2:5]
	global_load_dwordx4 v[28:31], v[116:117], off offset:2048
	global_load_dwordx4 v[36:39], v[118:119], off offset:2048
	s_waitcnt vmcnt(20)
	v_mfma_f32_16x16x32_bf16 v[2:5], v[40:43], v[44:47], v[2:5]
	global_load_dwordx4 v[40:43], v[116:117], off offset:2560
	global_load_dwordx4 v[44:47], v[118:119], off offset:2560
	s_waitcnt vmcnt(20)
	v_mfma_f32_16x16x32_bf16 v[2:5], v[48:51], v[52:55], v[2:5]
	global_load_dwordx4 v[48:51], v[116:117], off offset:3072
	global_load_dwordx4 v[52:55], v[118:119], off offset:3072
	s_waitcnt vmcnt(20)
	v_mfma_f32_16x16x32_bf16 v[2:5], v[56:59], v[60:63], v[2:5]
	global_load_dwordx4 v[56:59], v[116:117], off offset:3584
	global_load_dwordx4 v[60:63], v[118:119], off offset:3584
	s_waitcnt vmcnt(20)
	v_mfma_f32_16x16x32_bf16 v[2:5], v[64:67], v[68:71], v[2:5]
	global_load_dwordx4 v[64:67], v[120:121], off
	global_load_dwordx4 v[68:71], v[122:123], off
	s_waitcnt vmcnt(20)
	v_mfma_f32_16x16x32_bf16 v[2:5], v[72:75], v[76:79], v[2:5]
	global_load_dwordx4 v[72:75], v[120:121], off offset:512
	global_load_dwordx4 v[76:79], v[122:123], off offset:512
	s_waitcnt vmcnt(20)
	v_mfma_f32_16x16x32_bf16 v[2:5], v[80:83], v[84:87], v[2:5]
	global_load_dwordx4 v[80:83], v[120:121], off offset:1024
	global_load_dwordx4 v[84:87], v[122:123], off offset:1024
	s_waitcnt vmcnt(20)
	v_mfma_f32_16x16x32_bf16 v[2:5], v[88:91], v[92:95], v[2:5]
	global_load_dwordx4 v[88:91], v[120:121], off offset:1536
	global_load_dwordx4 v[92:95], v[122:123], off offset:1536
	s_waitcnt vmcnt(20)
	v_mfma_f32_16x16x32_bf16 v[2:5], v[96:99], v[100:103], v[2:5]
	global_load_dwordx4 v[96:99], v[120:121], off offset:2048
	global_load_dwordx4 v[100:103], v[122:123], off offset:2048
	s_waitcnt vmcnt(20)
	v_mfma_f32_16x16x32_bf16 v[2:5], v[104:107], v[108:111], v[2:5]
	global_load_dwordx4 v[104:107], v[120:121], off offset:2560
	global_load_dwordx4 v[108:111], v[122:123], off offset:2560
	s_waitcnt vmcnt(20)
	v_mfma_f32_16x16x32_bf16 v[2:5], v[20:23], v[24:27], v[2:5]
	s_waitcnt vmcnt(18)
	v_mfma_f32_16x16x32_bf16 v[2:5], v[28:31], v[36:39], v[2:5]
	s_waitcnt vmcnt(16)
	v_mfma_f32_16x16x32_bf16 v[2:5], v[40:43], v[44:47], v[2:5]
	s_waitcnt vmcnt(14)
	v_mfma_f32_16x16x32_bf16 v[2:5], v[48:51], v[52:55], v[2:5]
	s_waitcnt vmcnt(12)
	v_mfma_f32_16x16x32_bf16 v[2:5], v[56:59], v[60:63], v[2:5]
	s_waitcnt vmcnt(10)
	v_mfma_f32_16x16x32_bf16 v[2:5], v[64:67], v[68:71], v[2:5]
	s_waitcnt vmcnt(8)
	v_mfma_f32_16x16x32_bf16 v[2:5], v[72:75], v[76:79], v[2:5]
	s_waitcnt vmcnt(6)
	v_mfma_f32_16x16x32_bf16 v[2:5], v[80:83], v[84:87], v[2:5]
	s_waitcnt vmcnt(4)
	v_mfma_f32_16x16x32_bf16 v[2:5], v[88:91], v[92:95], v[2:5]
	s_waitcnt vmcnt(2)
	v_mfma_f32_16x16x32_bf16 v[2:5], v[96:99], v[100:103], v[2:5]
	s_waitcnt vmcnt(0)
	v_mfma_f32_16x16x32_bf16 v[2:5], v[104:107], v[108:111], v[2:5]
	s_add_i32 s18, s20, 168
	s_lshl_b32 s2, s20, 5
	s_addk_i32 s2, 0x1600
	s_add_i32 s24, s2, 0xffffff00
	s_lshl_b32 s24, s24, 1
	s_mov_b32 s25, 0
